# prep_v as barrier-free wave tasks on the waves without a prep_conv task (direct transposed 8-byte stores, no LDS)
# speedup vs baseline: 1.0900x; 1.0096x over previous
.Lpvw_entry:
	s_cmpk_ge_u32 s63, 0xc0
	s_cbranch_scc1 .Ls5l_back
	v_and_b32_e32 v74, 63, v206
	v_lshlrev_b32_e32 v72, 4, v74
	v_lshlrev_b32_e32 v78, 10, v74
	s_lshl_b32 s41, s63, 1
	s_add_u32 s41, s41, s40
	s_sub_u32 s41, s41, 6
	s_lshr_b32 s42, s41, 3
	s_and_b32 s43, s41, 7
	s_lshl_b32 s46, s42, 7
	s_lshl_b32 s47, s43, 4
	s_add_u32 s46, s46, s47
	s_mul_i32 s46, s46, 0x2440
	s_add_u32 s46, s46, 0x3a25c40
	s_add_u32 s44, s96, s46
	s_addc_u32 s45, s97, 0
	v_readlane_b32 s46, v237, 29
	v_readlane_b32 s47, v237, 30
	s_lshl_b32 s48, s36, 10
	s_add_u32 s46, s46, s48
	s_addc_u32 s47, s47, 0
	global_load_dwordx4 v[68:71], v72, s[46:47]
	global_load_dwordx4 v[4:7], v72, s[44:45]
	s_add_u32 s44, s44, 0x2440
	s_addc_u32 s45, s45, 0
	global_load_dwordx4 v[8:11], v72, s[44:45]
	s_add_u32 s44, s44, 0x2440
	s_addc_u32 s45, s45, 0
	global_load_dwordx4 v[12:15], v72, s[44:45]
	s_add_u32 s44, s44, 0x2440
	s_addc_u32 s45, s45, 0
	global_load_dwordx4 v[16:19], v72, s[44:45]
	s_add_u32 s44, s44, 0x2440
	s_addc_u32 s45, s45, 0
	global_load_dwordx4 v[20:23], v72, s[44:45]
	s_add_u32 s44, s44, 0x2440
	s_addc_u32 s45, s45, 0
	global_load_dwordx4 v[24:27], v72, s[44:45]
	s_add_u32 s44, s44, 0x2440
	s_addc_u32 s45, s45, 0
	global_load_dwordx4 v[28:31], v72, s[44:45]
	s_add_u32 s44, s44, 0x2440
	s_addc_u32 s45, s45, 0
	global_load_dwordx4 v[32:35], v72, s[44:45]
	s_add_u32 s44, s44, 0x2440
	s_addc_u32 s45, s45, 0
	global_load_dwordx4 v[36:39], v72, s[44:45]
	s_add_u32 s44, s44, 0x2440
	s_addc_u32 s45, s45, 0
	global_load_dwordx4 v[40:43], v72, s[44:45]
	s_add_u32 s44, s44, 0x2440
	s_addc_u32 s45, s45, 0
	global_load_dwordx4 v[44:47], v72, s[44:45]
	s_add_u32 s44, s44, 0x2440
	s_addc_u32 s45, s45, 0
	global_load_dwordx4 v[48:51], v72, s[44:45]
	s_add_u32 s44, s44, 0x2440
	s_addc_u32 s45, s45, 0
	global_load_dwordx4 v[52:55], v72, s[44:45]
	s_add_u32 s44, s44, 0x2440
	s_addc_u32 s45, s45, 0
	global_load_dwordx4 v[56:59], v72, s[44:45]
	s_add_u32 s44, s44, 0x2440
	s_addc_u32 s45, s45, 0
	global_load_dwordx4 v[60:63], v72, s[44:45]
	s_add_u32 s44, s44, 0x2440
	s_addc_u32 s45, s45, 0
	global_load_dwordx4 v[64:67], v72, s[44:45]
	s_lshl_b32 s46, s42, 16
	s_lshl_b32 s47, s43, 5
	s_add_u32 s46, s46, s47
	s_add_u32 s46, s46, 0xc784000
	s_add_u32 s44, s96, s46
	s_addc_u32 s45, s97, 0
	s_waitcnt vmcnt(0)
	s_mov_b32 s50, 0
.Lpvw_rows:
	v_mul_f32_e32 v80, 0x3d372713, v4
	v_mul_f32_e32 v80, v4, v80
	v_fma_f32 v80, v4, v80, v4
	v_mul_f32_e32 v80, 0x3f4c422a, v80
	v_add_f32_e32 v80, v80, v80
	v_mul_f32_e32 v80, 0x3fb8aa3b, v80
	v_exp_f32_e32 v80, v80
	v_mul_f32_e32 v81, 0.5, v4
	v_add_f32_e32 v80, 1.0, v80
	v_div_scale_f32 v82, s[100:101], v80, v80, 2.0
	v_rcp_f32_e32 v83, v82
	s_nop 0
	v_fma_f32 v84, -v82, v83, 1.0
	v_fmac_f32_e32 v83, v84, v83
	v_div_scale_f32 v84, vcc, 2.0, v80, 2.0
	v_mul_f32_e32 v85, v84, v83
	v_fma_f32 v86, -v82, v85, v84
	v_fmac_f32_e32 v85, v86, v83
	v_fma_f32 v82, -v82, v85, v84
	v_div_fmas_f32 v82, v82, v83, v85
	v_div_fixup_f32 v80, v82, v80, 2.0
	v_sub_f32_e32 v80, 1.0, v80
	v_add_f32_e32 v80, 1.0, v80
	v_mul_f32_e32 v4, v81, v80
	v_mul_f32_e32 v80, 0x3d372713, v5
	v_mul_f32_e32 v80, v5, v80
	v_fma_f32 v80, v5, v80, v5
	v_mul_f32_e32 v80, 0x3f4c422a, v80
	v_add_f32_e32 v80, v80, v80
	v_mul_f32_e32 v80, 0x3fb8aa3b, v80
	v_exp_f32_e32 v80, v80
	v_mul_f32_e32 v81, 0.5, v5
	v_add_f32_e32 v80, 1.0, v80
	v_div_scale_f32 v82, s[100:101], v80, v80, 2.0
	v_rcp_f32_e32 v83, v82
	s_nop 0
	v_fma_f32 v84, -v82, v83, 1.0
	v_fmac_f32_e32 v83, v84, v83
	v_div_scale_f32 v84, vcc, 2.0, v80, 2.0
	v_mul_f32_e32 v85, v84, v83
	v_fma_f32 v86, -v82, v85, v84
	v_fmac_f32_e32 v85, v86, v83
	v_fma_f32 v82, -v82, v85, v84
	v_div_fmas_f32 v82, v82, v83, v85
	v_div_fixup_f32 v80, v82, v80, 2.0
	v_sub_f32_e32 v80, 1.0, v80
	v_add_f32_e32 v80, 1.0, v80
	v_mul_f32_e32 v5, v81, v80
	v_mul_f32_e32 v80, 0x3d372713, v6
	v_mul_f32_e32 v80, v6, v80
	v_fma_f32 v80, v6, v80, v6
	v_mul_f32_e32 v80, 0x3f4c422a, v80
	v_add_f32_e32 v80, v80, v80
	v_mul_f32_e32 v80, 0x3fb8aa3b, v80
	v_exp_f32_e32 v80, v80
	v_mul_f32_e32 v81, 0.5, v6
	v_add_f32_e32 v80, 1.0, v80
	v_div_scale_f32 v82, s[100:101], v80, v80, 2.0
	v_rcp_f32_e32 v83, v82
	s_nop 0
	v_fma_f32 v84, -v82, v83, 1.0
	v_fmac_f32_e32 v83, v84, v83
	v_div_scale_f32 v84, vcc, 2.0, v80, 2.0
	v_mul_f32_e32 v85, v84, v83
	v_fma_f32 v86, -v82, v85, v84
	v_fmac_f32_e32 v85, v86, v83
	v_fma_f32 v82, -v82, v85, v84
	v_div_fmas_f32 v82, v82, v83, v85
	v_div_fixup_f32 v80, v82, v80, 2.0
	v_sub_f32_e32 v80, 1.0, v80
	v_add_f32_e32 v80, 1.0, v80
	v_mul_f32_e32 v6, v81, v80
	v_mul_f32_e32 v80, 0x3d372713, v7
	v_mul_f32_e32 v80, v7, v80
	v_fma_f32 v80, v7, v80, v7
	v_mul_f32_e32 v80, 0x3f4c422a, v80
	v_add_f32_e32 v80, v80, v80
	v_mul_f32_e32 v80, 0x3fb8aa3b, v80
	v_exp_f32_e32 v80, v80
	v_mul_f32_e32 v81, 0.5, v7
	v_add_f32_e32 v80, 1.0, v80
	v_div_scale_f32 v82, s[100:101], v80, v80, 2.0
	v_rcp_f32_e32 v83, v82
	s_nop 0
	v_fma_f32 v84, -v82, v83, 1.0
	v_fmac_f32_e32 v83, v84, v83
	v_div_scale_f32 v84, vcc, 2.0, v80, 2.0
	v_mul_f32_e32 v85, v84, v83
	v_fma_f32 v86, -v82, v85, v84
	v_fmac_f32_e32 v85, v86, v83
	v_fma_f32 v82, -v82, v85, v84
	v_div_fmas_f32 v82, v82, v83, v85
	v_div_fixup_f32 v80, v82, v80, 2.0
	v_sub_f32_e32 v80, 1.0, v80
	v_add_f32_e32 v80, 1.0, v80
	v_mul_f32_e32 v7, v81, v80
	v_mul_f32_e32 v73, v4, v4
	v_fmac_f32_e32 v73, v5, v5
	v_fmac_f32_e32 v73, v6, v6
	v_fmac_f32_e32 v73, v7, v7
	s_nop 1
	v_add_f32_dpp v73, v73, v73 row_shr:1 row_mask:0xf bank_mask:0xf bound_ctrl:0
	s_nop 1
	v_add_f32_dpp v73, v73, v73 row_shr:2 row_mask:0xf bank_mask:0xf bound_ctrl:0
	s_nop 1
	v_add_f32_dpp v73, v73, v73 row_shr:4 row_mask:0xf bank_mask:0xf bound_ctrl:0
	s_nop 1
	v_add_f32_dpp v73, v73, v73 row_shr:8 row_mask:0xf bank_mask:0xf bound_ctrl:0
	s_nop 1
	v_readlane_b32 s46, v73, 15
	v_readlane_b32 s47, v73, 31
	v_readlane_b32 s48, v73, 47
	v_readlane_b32 s49, v73, 63
	v_mov_b32_e32 v74, s46
	v_add_f32_e32 v74, s47, v74
	v_add_f32_e32 v74, s48, v74
	v_add_f32_e32 v74, s49, v74
	v_mov_b32_e32 v75, 0x358637bd
	v_fmac_f32_e32 v75, 0x3b800000, v74
	v_rsq_f32_e32 v75, v75
	s_nop 0
	v_mul_f32_e32 v4, v4, v75
	v_mul_f32_e32 v4, v4, v68
	v_mul_f32_e32 v5, v5, v75
	v_mul_f32_e32 v5, v5, v69
	v_mul_f32_e32 v6, v6, v75
	v_mul_f32_e32 v6, v6, v70
	v_mul_f32_e32 v7, v7, v75
	v_mul_f32_e32 v7, v7, v71
	v_mul_f32_e32 v80, 0x3d372713, v8
	v_mul_f32_e32 v80, v8, v80
	v_fma_f32 v80, v8, v80, v8
	v_mul_f32_e32 v80, 0x3f4c422a, v80
	v_add_f32_e32 v80, v80, v80
	v_mul_f32_e32 v80, 0x3fb8aa3b, v80
	v_exp_f32_e32 v80, v80
	v_mul_f32_e32 v81, 0.5, v8
	v_add_f32_e32 v80, 1.0, v80
	v_div_scale_f32 v82, s[100:101], v80, v80, 2.0
	v_rcp_f32_e32 v83, v82
	s_nop 0
	v_fma_f32 v84, -v82, v83, 1.0
	v_fmac_f32_e32 v83, v84, v83
	v_div_scale_f32 v84, vcc, 2.0, v80, 2.0
	v_mul_f32_e32 v85, v84, v83
	v_fma_f32 v86, -v82, v85, v84
	v_fmac_f32_e32 v85, v86, v83
	v_fma_f32 v82, -v82, v85, v84
	v_div_fmas_f32 v82, v82, v83, v85
	v_div_fixup_f32 v80, v82, v80, 2.0
	v_sub_f32_e32 v80, 1.0, v80
	v_add_f32_e32 v80, 1.0, v80
	v_mul_f32_e32 v8, v81, v80
	v_mul_f32_e32 v80, 0x3d372713, v9
	v_mul_f32_e32 v80, v9, v80
	v_fma_f32 v80, v9, v80, v9
	v_mul_f32_e32 v80, 0x3f4c422a, v80
	v_add_f32_e32 v80, v80, v80
	v_mul_f32_e32 v80, 0x3fb8aa3b, v80
	v_exp_f32_e32 v80, v80
	v_mul_f32_e32 v81, 0.5, v9
	v_add_f32_e32 v80, 1.0, v80
	v_div_scale_f32 v82, s[100:101], v80, v80, 2.0
	v_rcp_f32_e32 v83, v82
	s_nop 0
	v_fma_f32 v84, -v82, v83, 1.0
	v_fmac_f32_e32 v83, v84, v83
	v_div_scale_f32 v84, vcc, 2.0, v80, 2.0
	v_mul_f32_e32 v85, v84, v83
	v_fma_f32 v86, -v82, v85, v84
	v_fmac_f32_e32 v85, v86, v83
	v_fma_f32 v82, -v82, v85, v84
	v_div_fmas_f32 v82, v82, v83, v85
	v_div_fixup_f32 v80, v82, v80, 2.0
	v_sub_f32_e32 v80, 1.0, v80
	v_add_f32_e32 v80, 1.0, v80
	v_mul_f32_e32 v9, v81, v80
	v_mul_f32_e32 v80, 0x3d372713, v10
	v_mul_f32_e32 v80, v10, v80
	v_fma_f32 v80, v10, v80, v10
	v_mul_f32_e32 v80, 0x3f4c422a, v80
	v_add_f32_e32 v80, v80, v80
	v_mul_f32_e32 v80, 0x3fb8aa3b, v80
	v_exp_f32_e32 v80, v80
	v_mul_f32_e32 v81, 0.5, v10
	v_add_f32_e32 v80, 1.0, v80
	v_div_scale_f32 v82, s[100:101], v80, v80, 2.0
	v_rcp_f32_e32 v83, v82
	s_nop 0
	v_fma_f32 v84, -v82, v83, 1.0
	v_fmac_f32_e32 v83, v84, v83
	v_div_scale_f32 v84, vcc, 2.0, v80, 2.0
	v_mul_f32_e32 v85, v84, v83
	v_fma_f32 v86, -v82, v85, v84
	v_fmac_f32_e32 v85, v86, v83
	v_fma_f32 v82, -v82, v85, v84
	v_div_fmas_f32 v82, v82, v83, v85
	v_div_fixup_f32 v80, v82, v80, 2.0
	v_sub_f32_e32 v80, 1.0, v80
	v_add_f32_e32 v80, 1.0, v80
	v_mul_f32_e32 v10, v81, v80
	v_mul_f32_e32 v80, 0x3d372713, v11
	v_mul_f32_e32 v80, v11, v80
	v_fma_f32 v80, v11, v80, v11
	v_mul_f32_e32 v80, 0x3f4c422a, v80
	v_add_f32_e32 v80, v80, v80
	v_mul_f32_e32 v80, 0x3fb8aa3b, v80
	v_exp_f32_e32 v80, v80
	v_mul_f32_e32 v81, 0.5, v11
	v_add_f32_e32 v80, 1.0, v80
	v_div_scale_f32 v82, s[100:101], v80, v80, 2.0
	v_rcp_f32_e32 v83, v82
	s_nop 0
	v_fma_f32 v84, -v82, v83, 1.0
	v_fmac_f32_e32 v83, v84, v83
	v_div_scale_f32 v84, vcc, 2.0, v80, 2.0
	v_mul_f32_e32 v85, v84, v83
	v_fma_f32 v86, -v82, v85, v84
	v_fmac_f32_e32 v85, v86, v83
	v_fma_f32 v82, -v82, v85, v84
	v_div_fmas_f32 v82, v82, v83, v85
	v_div_fixup_f32 v80, v82, v80, 2.0
	v_sub_f32_e32 v80, 1.0, v80
	v_add_f32_e32 v80, 1.0, v80
	v_mul_f32_e32 v11, v81, v80
	v_mul_f32_e32 v73, v8, v8
	v_fmac_f32_e32 v73, v9, v9
	v_fmac_f32_e32 v73, v10, v10
	v_fmac_f32_e32 v73, v11, v11
	s_nop 1
	v_add_f32_dpp v73, v73, v73 row_shr:1 row_mask:0xf bank_mask:0xf bound_ctrl:0
	s_nop 1
	v_add_f32_dpp v73, v73, v73 row_shr:2 row_mask:0xf bank_mask:0xf bound_ctrl:0
	s_nop 1
	v_add_f32_dpp v73, v73, v73 row_shr:4 row_mask:0xf bank_mask:0xf bound_ctrl:0
	s_nop 1
	v_add_f32_dpp v73, v73, v73 row_shr:8 row_mask:0xf bank_mask:0xf bound_ctrl:0
	s_nop 1
	v_readlane_b32 s46, v73, 15
	v_readlane_b32 s47, v73, 31
	v_readlane_b32 s48, v73, 47
	v_readlane_b32 s49, v73, 63
	v_mov_b32_e32 v74, s46
	v_add_f32_e32 v74, s47, v74
	v_add_f32_e32 v74, s48, v74
	v_add_f32_e32 v74, s49, v74
	v_mov_b32_e32 v75, 0x358637bd
	v_fmac_f32_e32 v75, 0x3b800000, v74
	v_rsq_f32_e32 v75, v75
	s_nop 0
	v_mul_f32_e32 v8, v8, v75
	v_mul_f32_e32 v8, v8, v68
	v_mul_f32_e32 v9, v9, v75
	v_mul_f32_e32 v9, v9, v69
	v_mul_f32_e32 v10, v10, v75
	v_mul_f32_e32 v10, v10, v70
	v_mul_f32_e32 v11, v11, v75
	v_mul_f32_e32 v11, v11, v71
	v_mul_f32_e32 v80, 0x3d372713, v12
	v_mul_f32_e32 v80, v12, v80
	v_fma_f32 v80, v12, v80, v12
	v_mul_f32_e32 v80, 0x3f4c422a, v80
	v_add_f32_e32 v80, v80, v80
	v_mul_f32_e32 v80, 0x3fb8aa3b, v80
	v_exp_f32_e32 v80, v80
	v_mul_f32_e32 v81, 0.5, v12
	v_add_f32_e32 v80, 1.0, v80
	v_div_scale_f32 v82, s[100:101], v80, v80, 2.0
	v_rcp_f32_e32 v83, v82
	s_nop 0
	v_fma_f32 v84, -v82, v83, 1.0
	v_fmac_f32_e32 v83, v84, v83
	v_div_scale_f32 v84, vcc, 2.0, v80, 2.0
	v_mul_f32_e32 v85, v84, v83
	v_fma_f32 v86, -v82, v85, v84
	v_fmac_f32_e32 v85, v86, v83
	v_fma_f32 v82, -v82, v85, v84
	v_div_fmas_f32 v82, v82, v83, v85
	v_div_fixup_f32 v80, v82, v80, 2.0
	v_sub_f32_e32 v80, 1.0, v80
	v_add_f32_e32 v80, 1.0, v80
	v_mul_f32_e32 v12, v81, v80
	v_mul_f32_e32 v80, 0x3d372713, v13
	v_mul_f32_e32 v80, v13, v80
	v_fma_f32 v80, v13, v80, v13
	v_mul_f32_e32 v80, 0x3f4c422a, v80
	v_add_f32_e32 v80, v80, v80
	v_mul_f32_e32 v80, 0x3fb8aa3b, v80
	v_exp_f32_e32 v80, v80
	v_mul_f32_e32 v81, 0.5, v13
	v_add_f32_e32 v80, 1.0, v80
	v_div_scale_f32 v82, s[100:101], v80, v80, 2.0
	v_rcp_f32_e32 v83, v82
	s_nop 0
	v_fma_f32 v84, -v82, v83, 1.0
	v_fmac_f32_e32 v83, v84, v83
	v_div_scale_f32 v84, vcc, 2.0, v80, 2.0
	v_mul_f32_e32 v85, v84, v83
	v_fma_f32 v86, -v82, v85, v84
	v_fmac_f32_e32 v85, v86, v83
	v_fma_f32 v82, -v82, v85, v84
	v_div_fmas_f32 v82, v82, v83, v85
	v_div_fixup_f32 v80, v82, v80, 2.0
	v_sub_f32_e32 v80, 1.0, v80
	v_add_f32_e32 v80, 1.0, v80
	v_mul_f32_e32 v13, v81, v80
	v_mul_f32_e32 v80, 0x3d372713, v14
	v_mul_f32_e32 v80, v14, v80
	v_fma_f32 v80, v14, v80, v14
	v_mul_f32_e32 v80, 0x3f4c422a, v80
	v_add_f32_e32 v80, v80, v80
	v_mul_f32_e32 v80, 0x3fb8aa3b, v80
	v_exp_f32_e32 v80, v80
	v_mul_f32_e32 v81, 0.5, v14
	v_add_f32_e32 v80, 1.0, v80
	v_div_scale_f32 v82, s[100:101], v80, v80, 2.0
	v_rcp_f32_e32 v83, v82
	s_nop 0
	v_fma_f32 v84, -v82, v83, 1.0
	v_fmac_f32_e32 v83, v84, v83
	v_div_scale_f32 v84, vcc, 2.0, v80, 2.0
	v_mul_f32_e32 v85, v84, v83
	v_fma_f32 v86, -v82, v85, v84
	v_fmac_f32_e32 v85, v86, v83
	v_fma_f32 v82, -v82, v85, v84
	v_div_fmas_f32 v82, v82, v83, v85
	v_div_fixup_f32 v80, v82, v80, 2.0
	v_sub_f32_e32 v80, 1.0, v80
	v_add_f32_e32 v80, 1.0, v80
	v_mul_f32_e32 v14, v81, v80
	v_mul_f32_e32 v80, 0x3d372713, v15
	v_mul_f32_e32 v80, v15, v80
	v_fma_f32 v80, v15, v80, v15
	v_mul_f32_e32 v80, 0x3f4c422a, v80
	v_add_f32_e32 v80, v80, v80
	v_mul_f32_e32 v80, 0x3fb8aa3b, v80
	v_exp_f32_e32 v80, v80
	v_mul_f32_e32 v81, 0.5, v15
	v_add_f32_e32 v80, 1.0, v80
	v_div_scale_f32 v82, s[100:101], v80, v80, 2.0
	v_rcp_f32_e32 v83, v82
	s_nop 0
	v_fma_f32 v84, -v82, v83, 1.0
	v_fmac_f32_e32 v83, v84, v83
	v_div_scale_f32 v84, vcc, 2.0, v80, 2.0
	v_mul_f32_e32 v85, v84, v83
	v_fma_f32 v86, -v82, v85, v84
	v_fmac_f32_e32 v85, v86, v83
	v_fma_f32 v82, -v82, v85, v84
	v_div_fmas_f32 v82, v82, v83, v85
	v_div_fixup_f32 v80, v82, v80, 2.0
	v_sub_f32_e32 v80, 1.0, v80
	v_add_f32_e32 v80, 1.0, v80
	v_mul_f32_e32 v15, v81, v80
	v_mul_f32_e32 v73, v12, v12
	v_fmac_f32_e32 v73, v13, v13
	v_fmac_f32_e32 v73, v14, v14
	v_fmac_f32_e32 v73, v15, v15
	s_nop 1
	v_add_f32_dpp v73, v73, v73 row_shr:1 row_mask:0xf bank_mask:0xf bound_ctrl:0
	s_nop 1
	v_add_f32_dpp v73, v73, v73 row_shr:2 row_mask:0xf bank_mask:0xf bound_ctrl:0
	s_nop 1
	v_add_f32_dpp v73, v73, v73 row_shr:4 row_mask:0xf bank_mask:0xf bound_ctrl:0
	s_nop 1
	v_add_f32_dpp v73, v73, v73 row_shr:8 row_mask:0xf bank_mask:0xf bound_ctrl:0
	s_nop 1
	v_readlane_b32 s46, v73, 15
	v_readlane_b32 s47, v73, 31
	v_readlane_b32 s48, v73, 47
	v_readlane_b32 s49, v73, 63
	v_mov_b32_e32 v74, s46
	v_add_f32_e32 v74, s47, v74
	v_add_f32_e32 v74, s48, v74
	v_add_f32_e32 v74, s49, v74
	v_mov_b32_e32 v75, 0x358637bd
	v_fmac_f32_e32 v75, 0x3b800000, v74
	v_rsq_f32_e32 v75, v75
	s_nop 0
	v_mul_f32_e32 v12, v12, v75
	v_mul_f32_e32 v12, v12, v68
	v_mul_f32_e32 v13, v13, v75
	v_mul_f32_e32 v13, v13, v69
	v_mul_f32_e32 v14, v14, v75
	v_mul_f32_e32 v14, v14, v70
	v_mul_f32_e32 v15, v15, v75
	v_mul_f32_e32 v15, v15, v71
	v_mul_f32_e32 v80, 0x3d372713, v16
	v_mul_f32_e32 v80, v16, v80
	v_fma_f32 v80, v16, v80, v16
	v_mul_f32_e32 v80, 0x3f4c422a, v80
	v_add_f32_e32 v80, v80, v80
	v_mul_f32_e32 v80, 0x3fb8aa3b, v80
	v_exp_f32_e32 v80, v80
	v_mul_f32_e32 v81, 0.5, v16
	v_add_f32_e32 v80, 1.0, v80
	v_div_scale_f32 v82, s[100:101], v80, v80, 2.0
	v_rcp_f32_e32 v83, v82
	s_nop 0
	v_fma_f32 v84, -v82, v83, 1.0
	v_fmac_f32_e32 v83, v84, v83
	v_div_scale_f32 v84, vcc, 2.0, v80, 2.0
	v_mul_f32_e32 v85, v84, v83
	v_fma_f32 v86, -v82, v85, v84
	v_fmac_f32_e32 v85, v86, v83
	v_fma_f32 v82, -v82, v85, v84
	v_div_fmas_f32 v82, v82, v83, v85
	v_div_fixup_f32 v80, v82, v80, 2.0
	v_sub_f32_e32 v80, 1.0, v80
	v_add_f32_e32 v80, 1.0, v80
	v_mul_f32_e32 v16, v81, v80
	v_mul_f32_e32 v80, 0x3d372713, v17
	v_mul_f32_e32 v80, v17, v80
	v_fma_f32 v80, v17, v80, v17
	v_mul_f32_e32 v80, 0x3f4c422a, v80
	v_add_f32_e32 v80, v80, v80
	v_mul_f32_e32 v80, 0x3fb8aa3b, v80
	v_exp_f32_e32 v80, v80
	v_mul_f32_e32 v81, 0.5, v17
	v_add_f32_e32 v80, 1.0, v80
	v_div_scale_f32 v82, s[100:101], v80, v80, 2.0
	v_rcp_f32_e32 v83, v82
	s_nop 0
	v_fma_f32 v84, -v82, v83, 1.0
	v_fmac_f32_e32 v83, v84, v83
	v_div_scale_f32 v84, vcc, 2.0, v80, 2.0
	v_mul_f32_e32 v85, v84, v83
	v_fma_f32 v86, -v82, v85, v84
	v_fmac_f32_e32 v85, v86, v83
	v_fma_f32 v82, -v82, v85, v84
	v_div_fmas_f32 v82, v82, v83, v85
	v_div_fixup_f32 v80, v82, v80, 2.0
	v_sub_f32_e32 v80, 1.0, v80
	v_add_f32_e32 v80, 1.0, v80
	v_mul_f32_e32 v17, v81, v80
	v_mul_f32_e32 v80, 0x3d372713, v18
	v_mul_f32_e32 v80, v18, v80
	v_fma_f32 v80, v18, v80, v18
	v_mul_f32_e32 v80, 0x3f4c422a, v80
	v_add_f32_e32 v80, v80, v80
	v_mul_f32_e32 v80, 0x3fb8aa3b, v80
	v_exp_f32_e32 v80, v80
	v_mul_f32_e32 v81, 0.5, v18
	v_add_f32_e32 v80, 1.0, v80
	v_div_scale_f32 v82, s[100:101], v80, v80, 2.0
	v_rcp_f32_e32 v83, v82
	s_nop 0
	v_fma_f32 v84, -v82, v83, 1.0
	v_fmac_f32_e32 v83, v84, v83
	v_div_scale_f32 v84, vcc, 2.0, v80, 2.0
	v_mul_f32_e32 v85, v84, v83
	v_fma_f32 v86, -v82, v85, v84
	v_fmac_f32_e32 v85, v86, v83
	v_fma_f32 v82, -v82, v85, v84
	v_div_fmas_f32 v82, v82, v83, v85
	v_div_fixup_f32 v80, v82, v80, 2.0
	v_sub_f32_e32 v80, 1.0, v80
	v_add_f32_e32 v80, 1.0, v80
	v_mul_f32_e32 v18, v81, v80
	v_mul_f32_e32 v80, 0x3d372713, v19
	v_mul_f32_e32 v80, v19, v80
	v_fma_f32 v80, v19, v80, v19
	v_mul_f32_e32 v80, 0x3f4c422a, v80
	v_add_f32_e32 v80, v80, v80
	v_mul_f32_e32 v80, 0x3fb8aa3b, v80
	v_exp_f32_e32 v80, v80
	v_mul_f32_e32 v81, 0.5, v19
	v_add_f32_e32 v80, 1.0, v80
	v_div_scale_f32 v82, s[100:101], v80, v80, 2.0
	v_rcp_f32_e32 v83, v82
	s_nop 0
	v_fma_f32 v84, -v82, v83, 1.0
	v_fmac_f32_e32 v83, v84, v83
	v_div_scale_f32 v84, vcc, 2.0, v80, 2.0
	v_mul_f32_e32 v85, v84, v83
	v_fma_f32 v86, -v82, v85, v84
	v_fmac_f32_e32 v85, v86, v83
	v_fma_f32 v82, -v82, v85, v84
	v_div_fmas_f32 v82, v82, v83, v85
	v_div_fixup_f32 v80, v82, v80, 2.0
	v_sub_f32_e32 v80, 1.0, v80
	v_add_f32_e32 v80, 1.0, v80
	v_mul_f32_e32 v19, v81, v80
	v_mul_f32_e32 v73, v16, v16
	v_fmac_f32_e32 v73, v17, v17
	v_fmac_f32_e32 v73, v18, v18
	v_fmac_f32_e32 v73, v19, v19
	s_nop 1
	v_add_f32_dpp v73, v73, v73 row_shr:1 row_mask:0xf bank_mask:0xf bound_ctrl:0
	s_nop 1
	v_add_f32_dpp v73, v73, v73 row_shr:2 row_mask:0xf bank_mask:0xf bound_ctrl:0
	s_nop 1
	v_add_f32_dpp v73, v73, v73 row_shr:4 row_mask:0xf bank_mask:0xf bound_ctrl:0
	s_nop 1
	v_add_f32_dpp v73, v73, v73 row_shr:8 row_mask:0xf bank_mask:0xf bound_ctrl:0
	s_nop 1
	v_readlane_b32 s46, v73, 15
	v_readlane_b32 s47, v73, 31
	v_readlane_b32 s48, v73, 47
	v_readlane_b32 s49, v73, 63
	v_mov_b32_e32 v74, s46
	v_add_f32_e32 v74, s47, v74
	v_add_f32_e32 v74, s48, v74
	v_add_f32_e32 v74, s49, v74
	v_mov_b32_e32 v75, 0x358637bd
	v_fmac_f32_e32 v75, 0x3b800000, v74
	v_rsq_f32_e32 v75, v75
	s_nop 0
	v_mul_f32_e32 v16, v16, v75
	v_mul_f32_e32 v16, v16, v68
	v_mul_f32_e32 v17, v17, v75
	v_mul_f32_e32 v17, v17, v69
	v_mul_f32_e32 v18, v18, v75
	v_mul_f32_e32 v18, v18, v70
	v_mul_f32_e32 v19, v19, v75
	v_mul_f32_e32 v19, v19, v71
	v_cvt_pk_bf16_f32 v88, v4, v8
	v_cvt_pk_bf16_f32 v89, v12, v16
	global_store_dwordx2 v78, v[88:89], s[44:45]
	s_nop 0
	v_cvt_pk_bf16_f32 v88, v5, v9
	v_cvt_pk_bf16_f32 v89, v13, v17
	global_store_dwordx2 v78, v[88:89], s[44:45] offset:256
	s_nop 0
	v_cvt_pk_bf16_f32 v88, v6, v10
	v_cvt_pk_bf16_f32 v89, v14, v18
	global_store_dwordx2 v78, v[88:89], s[44:45] offset:512
	s_nop 0
	v_cvt_pk_bf16_f32 v88, v7, v11
	v_cvt_pk_bf16_f32 v89, v15, v19
	global_store_dwordx2 v78, v[88:89], s[44:45] offset:768
	s_nop 0
	s_add_u32 s50, s50, 1
	s_cmp_eq_u32 s50, 4
	s_cbranch_scc1 .Ls5l_back
	s_add_u32 s44, s44, 8
	s_addc_u32 s45, s45, 0
	v_mov_b32_e32 v4, v20
	v_mov_b32_e32 v5, v21
	v_mov_b32_e32 v6, v22
	v_mov_b32_e32 v7, v23
	v_mov_b32_e32 v8, v24
	v_mov_b32_e32 v9, v25
	v_mov_b32_e32 v10, v26
	v_mov_b32_e32 v11, v27
	v_mov_b32_e32 v12, v28
	v_mov_b32_e32 v13, v29
	v_mov_b32_e32 v14, v30
	v_mov_b32_e32 v15, v31
	v_mov_b32_e32 v16, v32
	v_mov_b32_e32 v17, v33
	v_mov_b32_e32 v18, v34
	v_mov_b32_e32 v19, v35
	v_mov_b32_e32 v20, v36
	v_mov_b32_e32 v21, v37
	v_mov_b32_e32 v22, v38
	v_mov_b32_e32 v23, v39
	v_mov_b32_e32 v24, v40
	v_mov_b32_e32 v25, v41
	v_mov_b32_e32 v26, v42
	v_mov_b32_e32 v27, v43
	v_mov_b32_e32 v28, v44
	v_mov_b32_e32 v29, v45
	v_mov_b32_e32 v30, v46
	v_mov_b32_e32 v31, v47
	v_mov_b32_e32 v32, v48
	v_mov_b32_e32 v33, v49
	v_mov_b32_e32 v34, v50
	v_mov_b32_e32 v35, v51
	v_mov_b32_e32 v36, v52
	v_mov_b32_e32 v37, v53
	v_mov_b32_e32 v38, v54
	v_mov_b32_e32 v39, v55
	v_mov_b32_e32 v40, v56
	v_mov_b32_e32 v41, v57
	v_mov_b32_e32 v42, v58
	v_mov_b32_e32 v43, v59
	v_mov_b32_e32 v44, v60
	v_mov_b32_e32 v45, v61
	v_mov_b32_e32 v46, v62
	v_mov_b32_e32 v47, v63
	v_mov_b32_e32 v48, v64
	v_mov_b32_e32 v49, v65
	v_mov_b32_e32 v50, v66
	v_mov_b32_e32 v51, v67
	s_branch .Lpvw_rows
